# pool-GEMM epilogue variant: up-front gate loads, stores interleaved after each group (vmcnt 15 throughout)
# baseline (speedup 1.0000x reference)
; __device__ __forceinline__ float bflo(unsigned w) { return __uint_as_float(w << 16); }
; __device__ __forceinline__ float bfhi(unsigned w) { return __uint_as_float(w & 0xffff0000u); }
;     __device__ __forceinline__ void operator()(f32x4 (&acc)[2][2][4][2], const Unit& u, int wr, int wc, int fr, int fq) const {
;     ...
;         for (int ai = 0; ai < 2; ++ai)
; #pragma unroll
;             for (int m = 0; m < 4; ++m) { const size_t row = (size_t)(row0 + ai * HALF + m * 16);
; #pragma unroll
;                 for (int bj = 0; bj < 2; ++bj) { const int col = col0 + bj * HALF;
;                     const u32x4 gt = *(const u32x4*)(HM + row * HMW + C_AGATE + col);
;                     const f32x4 v0 = acc[ai][bj][m][0], v1 = acc[ai][bj][m][1];
;                     u32x4 w; w.x = pk2(v0[0] * bflo(gt.x), v0[1] * bfhi(gt.x)); w.y = pk2(v0[2] * bflo(gt.y), v0[3] * bfhi(gt.y));
;                     w.z = pk2(v1[0] * bflo(gt.z), v1[1] * bfhi(gt.z)); w.w = pk2(v1[2] * bflo(gt.w), v1[3] * bfhi(gt.w));
;                     *(u32x4*)(YA + row * 1024 + col) = w; } }
.LBB0_623:
	s_mov_b64 s[86:87], -1
	v_lshl_add_u32 v234, v152, 11, v153
	s_waitcnt vmcnt(15)
	v_lshlrev_b32_e32 v226, 16, v148
	v_and_b32_e32 v227, 0xffff0000, v148
	v_lshlrev_b32_e32 v228, 16, v149
	v_and_b32_e32 v229, 0xffff0000, v149
	v_lshlrev_b32_e32 v230, 16, v150
	v_and_b32_e32 v231, 0xffff0000, v150
	v_lshlrev_b32_e32 v232, 16, v151
	v_and_b32_e32 v233, 0xffff0000, v151
	v_mul_f32_e32 v126, v126, v226
	v_mul_f32_e32 v127, v127, v227
	v_mul_f32_e32 v128, v128, v228
	v_mul_f32_e32 v129, v129, v229
	v_mul_f32_e32 v122, v122, v230
	v_mul_f32_e32 v123, v123, v231
	v_mul_f32_e32 v124, v124, v232
	v_mul_f32_e32 v125, v125, v233
	v_cvt_pk_bf16_f32 v148, v126, v127
	v_cvt_pk_bf16_f32 v149, v128, v129
	v_cvt_pk_bf16_f32 v150, v122, v123
	v_cvt_pk_bf16_f32 v151, v124, v125
	global_store_dwordx4 v234, v[148:151], s[38:39]
	s_waitcnt vmcnt(15)
	v_lshlrev_b32_e32 v226, 16, v158
	v_and_b32_e32 v227, 0xffff0000, v158
	v_lshlrev_b32_e32 v228, 16, v159
	v_and_b32_e32 v229, 0xffff0000, v159
	v_lshlrev_b32_e32 v230, 16, v160
	v_and_b32_e32 v231, 0xffff0000, v160
	v_lshlrev_b32_e32 v232, 16, v161
	v_and_b32_e32 v233, 0xffff0000, v161
	v_mul_f32_e32 v118, v118, v226
	v_mul_f32_e32 v119, v119, v227
	v_mul_f32_e32 v120, v120, v228
	v_mul_f32_e32 v121, v121, v229
	v_mul_f32_e32 v114, v114, v230
	v_mul_f32_e32 v115, v115, v231
	v_mul_f32_e32 v116, v116, v232
	v_mul_f32_e32 v117, v117, v233
	v_cvt_pk_bf16_f32 v158, v118, v119
	v_cvt_pk_bf16_f32 v159, v120, v121
	v_cvt_pk_bf16_f32 v160, v114, v115
	v_cvt_pk_bf16_f32 v161, v116, v117
	global_store_dwordx4 v234, v[158:161], s[38:39] offset:256
	s_waitcnt vmcnt(15)
	v_lshlrev_b32_e32 v226, 16, v162
	v_and_b32_e32 v227, 0xffff0000, v162
	v_lshlrev_b32_e32 v228, 16, v163
	v_and_b32_e32 v229, 0xffff0000, v163
	v_lshlrev_b32_e32 v230, 16, v164
	v_and_b32_e32 v231, 0xffff0000, v164
	v_lshlrev_b32_e32 v232, 16, v165
	v_and_b32_e32 v233, 0xffff0000, v165
	v_mul_f32_e32 v110, v110, v226
	v_mul_f32_e32 v111, v111, v227
	v_mul_f32_e32 v112, v112, v228
	v_mul_f32_e32 v113, v113, v229
	v_mul_f32_e32 v106, v106, v230
	v_mul_f32_e32 v107, v107, v231
	v_mul_f32_e32 v108, v108, v232
	v_mul_f32_e32 v109, v109, v233
	v_add_u32_e32 v235, 0x8000, v234
	v_cvt_pk_bf16_f32 v162, v110, v111
	v_cvt_pk_bf16_f32 v163, v112, v113
	v_cvt_pk_bf16_f32 v164, v106, v107
	v_cvt_pk_bf16_f32 v165, v108, v109
	global_store_dwordx4 v235, v[162:165], s[38:39]
	s_waitcnt vmcnt(15)
	v_lshlrev_b32_e32 v226, 16, v174
	v_and_b32_e32 v227, 0xffff0000, v174
	v_lshlrev_b32_e32 v228, 16, v175
	v_and_b32_e32 v229, 0xffff0000, v175
	v_lshlrev_b32_e32 v230, 16, v176
	v_and_b32_e32 v231, 0xffff0000, v176
	v_lshlrev_b32_e32 v232, 16, v177
	v_and_b32_e32 v233, 0xffff0000, v177
	v_mul_f32_e32 v102, v102, v226
	v_mul_f32_e32 v103, v103, v227
	v_mul_f32_e32 v104, v104, v228
	v_mul_f32_e32 v105, v105, v229
	v_mul_f32_e32 v98, v98, v230
	v_mul_f32_e32 v99, v99, v231
	v_mul_f32_e32 v100, v100, v232
	v_mul_f32_e32 v101, v101, v233
	v_add_u32_e32 v235, 0x8000, v234
	v_cvt_pk_bf16_f32 v174, v102, v103
	v_cvt_pk_bf16_f32 v175, v104, v105
	v_cvt_pk_bf16_f32 v176, v98, v99
	v_cvt_pk_bf16_f32 v177, v100, v101
	global_store_dwordx4 v235, v[174:177], s[38:39] offset:256
	s_waitcnt vmcnt(15)
	v_lshlrev_b32_e32 v226, 16, v178
	v_and_b32_e32 v227, 0xffff0000, v178
	v_lshlrev_b32_e32 v228, 16, v179
	v_and_b32_e32 v229, 0xffff0000, v179
	v_lshlrev_b32_e32 v230, 16, v180
	v_and_b32_e32 v231, 0xffff0000, v180
	v_lshlrev_b32_e32 v232, 16, v181
	v_and_b32_e32 v233, 0xffff0000, v181
	v_mul_f32_e32 v94, v94, v226
	v_mul_f32_e32 v95, v95, v227
	v_mul_f32_e32 v96, v96, v228
	v_mul_f32_e32 v97, v97, v229
	v_mul_f32_e32 v90, v90, v230
	v_mul_f32_e32 v91, v91, v231
	v_mul_f32_e32 v92, v92, v232
	v_mul_f32_e32 v93, v93, v233
	v_add_u32_e32 v235, 0x10000, v234
	v_cvt_pk_bf16_f32 v178, v94, v95
	v_cvt_pk_bf16_f32 v179, v96, v97
	v_cvt_pk_bf16_f32 v180, v90, v91
	v_cvt_pk_bf16_f32 v181, v92, v93
	global_store_dwordx4 v235, v[178:181], s[38:39]
	s_waitcnt vmcnt(15)
	v_lshlrev_b32_e32 v226, 16, v182
	v_and_b32_e32 v227, 0xffff0000, v182
	v_lshlrev_b32_e32 v228, 16, v183
	v_and_b32_e32 v229, 0xffff0000, v183
	v_lshlrev_b32_e32 v230, 16, v184
	v_and_b32_e32 v231, 0xffff0000, v184
	v_lshlrev_b32_e32 v232, 16, v185
	v_and_b32_e32 v233, 0xffff0000, v185
	v_mul_f32_e32 v86, v86, v226
	v_mul_f32_e32 v87, v87, v227
	v_mul_f32_e32 v88, v88, v228
	v_mul_f32_e32 v89, v89, v229
	v_mul_f32_e32 v82, v82, v230
	v_mul_f32_e32 v83, v83, v231
	v_mul_f32_e32 v84, v84, v232
	v_mul_f32_e32 v85, v85, v233
	v_add_u32_e32 v235, 0x10000, v234
	v_cvt_pk_bf16_f32 v182, v86, v87
	v_cvt_pk_bf16_f32 v183, v88, v89
	v_cvt_pk_bf16_f32 v184, v82, v83
	v_cvt_pk_bf16_f32 v185, v84, v85
	global_store_dwordx4 v235, v[182:185], s[38:39] offset:256
	s_waitcnt vmcnt(15)
	v_lshlrev_b32_e32 v226, 16, v186
	v_and_b32_e32 v227, 0xffff0000, v186
	v_lshlrev_b32_e32 v228, 16, v187
	v_and_b32_e32 v229, 0xffff0000, v187
	v_lshlrev_b32_e32 v230, 16, v188
	v_and_b32_e32 v231, 0xffff0000, v188
	v_lshlrev_b32_e32 v232, 16, v189
	v_and_b32_e32 v233, 0xffff0000, v189
	v_mul_f32_e32 v78, v78, v226
	v_mul_f32_e32 v79, v79, v227
	v_mul_f32_e32 v80, v80, v228
	v_mul_f32_e32 v81, v81, v229
	v_mul_f32_e32 v74, v74, v230
	v_mul_f32_e32 v75, v75, v231
	v_mul_f32_e32 v76, v76, v232
	v_mul_f32_e32 v77, v77, v233
	v_add_u32_e32 v235, 0x18000, v234
	v_cvt_pk_bf16_f32 v186, v78, v79
	v_cvt_pk_bf16_f32 v187, v80, v81
	v_cvt_pk_bf16_f32 v188, v74, v75
	v_cvt_pk_bf16_f32 v189, v76, v77
	global_store_dwordx4 v235, v[186:189], s[38:39]
	s_waitcnt vmcnt(15)
; __device__ __forceinline__ float bflo(unsigned w) { return __uint_as_float(w << 16); }
; __device__ __forceinline__ float bfhi(unsigned w) { return __uint_as_float(w & 0xffff0000u); }
;     __device__ __forceinline__ void operator()(f32x4 (&acc)[2][2][4][2], const Unit& u, int wr, int wc, int fr, int fq) const {
;     ...
;                     const u32x4 gt = *(const u32x4*)(HM + row * HMW + C_AGATE + col);
;                     const f32x4 v0 = acc[ai][bj][m][0], v1 = acc[ai][bj][m][1];
;                     u32x4 w; w.x = pk2(v0[0] * bflo(gt.x), v0[1] * bfhi(gt.x)); w.y = pk2(v0[2] * bflo(gt.y), v0[3] * bfhi(gt.y));
;                     w.z = pk2(v1[0] * bflo(gt.z), v1[1] * bfhi(gt.z)); w.w = pk2(v1[2] * bflo(gt.w), v1[3] * bfhi(gt.w));
;                     *(u32x4*)(YA + row * 1024 + col) = w; } }
	v_lshlrev_b32_e32 v226, 16, v190
	v_and_b32_e32 v227, 0xffff0000, v190
	v_lshlrev_b32_e32 v228, 16, v191
	v_and_b32_e32 v229, 0xffff0000, v191
	v_lshlrev_b32_e32 v230, 16, v192
	v_and_b32_e32 v231, 0xffff0000, v192
	v_lshlrev_b32_e32 v232, 16, v193
	v_and_b32_e32 v233, 0xffff0000, v193
	v_mul_f32_e32 v70, v70, v226
	v_mul_f32_e32 v71, v71, v227
	v_mul_f32_e32 v72, v72, v228
	v_mul_f32_e32 v73, v73, v229
	v_mul_f32_e32 v66, v66, v230
	v_mul_f32_e32 v67, v67, v231
	v_mul_f32_e32 v68, v68, v232
	v_mul_f32_e32 v69, v69, v233
	v_add_u32_e32 v235, 0x18000, v234
	v_cvt_pk_bf16_f32 v190, v70, v71
	v_cvt_pk_bf16_f32 v191, v72, v73
	v_cvt_pk_bf16_f32 v192, v66, v67
	v_cvt_pk_bf16_f32 v193, v68, v69
	global_store_dwordx4 v235, v[190:193], s[38:39] offset:256
	s_waitcnt vmcnt(15)
	v_lshlrev_b32_e32 v226, 16, v194
	v_and_b32_e32 v227, 0xffff0000, v194
	v_lshlrev_b32_e32 v228, 16, v195
	v_and_b32_e32 v229, 0xffff0000, v195
	v_lshlrev_b32_e32 v230, 16, v196
	v_and_b32_e32 v231, 0xffff0000, v196
	v_lshlrev_b32_e32 v232, 16, v197
	v_and_b32_e32 v233, 0xffff0000, v197
	v_mul_f32_e32 v62, v62, v226
	v_mul_f32_e32 v63, v63, v227
	v_mul_f32_e32 v64, v64, v228
	v_mul_f32_e32 v65, v65, v229
	v_mul_f32_e32 v58, v58, v230
	v_mul_f32_e32 v59, v59, v231
	v_mul_f32_e32 v60, v60, v232
	v_mul_f32_e32 v61, v61, v233
	v_add_u32_e32 v235, 0x40000, v234
	v_cvt_pk_bf16_f32 v194, v62, v63
	v_cvt_pk_bf16_f32 v195, v64, v65
	v_cvt_pk_bf16_f32 v196, v58, v59
	v_cvt_pk_bf16_f32 v197, v60, v61
	global_store_dwordx4 v235, v[194:197], s[38:39]
	s_waitcnt vmcnt(15)
	v_lshlrev_b32_e32 v226, 16, v198
	v_and_b32_e32 v227, 0xffff0000, v198
	v_lshlrev_b32_e32 v228, 16, v199
	v_and_b32_e32 v229, 0xffff0000, v199
	v_lshlrev_b32_e32 v230, 16, v200
	v_and_b32_e32 v231, 0xffff0000, v200
	v_lshlrev_b32_e32 v232, 16, v201
	v_and_b32_e32 v233, 0xffff0000, v201
	v_mul_f32_e32 v54, v54, v226
	v_mul_f32_e32 v55, v55, v227
	v_mul_f32_e32 v56, v56, v228
	v_mul_f32_e32 v57, v57, v229
	v_mul_f32_e32 v50, v50, v230
	v_mul_f32_e32 v51, v51, v231
	v_mul_f32_e32 v52, v52, v232
	v_mul_f32_e32 v53, v53, v233
	v_add_u32_e32 v235, 0x40000, v234
	v_cvt_pk_bf16_f32 v198, v54, v55
	v_cvt_pk_bf16_f32 v199, v56, v57
	v_cvt_pk_bf16_f32 v200, v50, v51
	v_cvt_pk_bf16_f32 v201, v52, v53
	global_store_dwordx4 v235, v[198:201], s[38:39] offset:256
	s_waitcnt vmcnt(15)
	v_lshlrev_b32_e32 v226, 16, v202
	v_and_b32_e32 v227, 0xffff0000, v202
	v_lshlrev_b32_e32 v228, 16, v203
	v_and_b32_e32 v229, 0xffff0000, v203
	v_lshlrev_b32_e32 v230, 16, v204
	v_and_b32_e32 v231, 0xffff0000, v204
	v_lshlrev_b32_e32 v232, 16, v205
	v_and_b32_e32 v233, 0xffff0000, v205
	v_mul_f32_e32 v46, v46, v226
	v_mul_f32_e32 v47, v47, v227
	v_mul_f32_e32 v48, v48, v228
	v_mul_f32_e32 v49, v49, v229
	v_mul_f32_e32 v42, v42, v230
	v_mul_f32_e32 v43, v43, v231
	v_mul_f32_e32 v44, v44, v232
	v_mul_f32_e32 v45, v45, v233
	v_add_u32_e32 v235, 0x48000, v234
	v_cvt_pk_bf16_f32 v202, v46, v47
	v_cvt_pk_bf16_f32 v203, v48, v49
	v_cvt_pk_bf16_f32 v204, v42, v43
	v_cvt_pk_bf16_f32 v205, v44, v45
	global_store_dwordx4 v235, v[202:205], s[38:39]
	s_waitcnt vmcnt(15)
	v_lshlrev_b32_e32 v226, 16, v206
	v_and_b32_e32 v227, 0xffff0000, v206
	v_lshlrev_b32_e32 v228, 16, v207
	v_and_b32_e32 v229, 0xffff0000, v207
	v_lshlrev_b32_e32 v230, 16, v208
	v_and_b32_e32 v231, 0xffff0000, v208
	v_lshlrev_b32_e32 v232, 16, v209
	v_and_b32_e32 v233, 0xffff0000, v209
	v_mul_f32_e32 v38, v38, v226
	v_mul_f32_e32 v39, v39, v227
	v_mul_f32_e32 v40, v40, v228
	v_mul_f32_e32 v41, v41, v229
	v_mul_f32_e32 v34, v34, v230
	v_mul_f32_e32 v35, v35, v231
	v_mul_f32_e32 v36, v36, v232
	v_mul_f32_e32 v37, v37, v233
	v_add_u32_e32 v235, 0x48000, v234
	v_cvt_pk_bf16_f32 v206, v38, v39
	v_cvt_pk_bf16_f32 v207, v40, v41
	v_cvt_pk_bf16_f32 v208, v34, v35
	v_cvt_pk_bf16_f32 v209, v36, v37
	global_store_dwordx4 v235, v[206:209], s[38:39] offset:256
	s_waitcnt vmcnt(15)
	v_lshlrev_b32_e32 v226, 16, v210
	v_and_b32_e32 v227, 0xffff0000, v210
	v_lshlrev_b32_e32 v228, 16, v211
	v_and_b32_e32 v229, 0xffff0000, v211
	v_lshlrev_b32_e32 v230, 16, v212
	v_and_b32_e32 v231, 0xffff0000, v212
	v_lshlrev_b32_e32 v232, 16, v213
	v_and_b32_e32 v233, 0xffff0000, v213
	v_mul_f32_e32 v30, v30, v226
	v_mul_f32_e32 v31, v31, v227
	v_mul_f32_e32 v32, v32, v228
	v_mul_f32_e32 v33, v33, v229
	v_mul_f32_e32 v26, v26, v230
	v_mul_f32_e32 v27, v27, v231
	v_mul_f32_e32 v28, v28, v232
	v_mul_f32_e32 v29, v29, v233
	v_add_u32_e32 v235, 0x50000, v234
	v_cvt_pk_bf16_f32 v210, v30, v31
	v_cvt_pk_bf16_f32 v211, v32, v33
	v_cvt_pk_bf16_f32 v212, v26, v27
	v_cvt_pk_bf16_f32 v213, v28, v29
	global_store_dwordx4 v235, v[210:213], s[38:39]
	s_waitcnt vmcnt(15)
	v_lshlrev_b32_e32 v226, 16, v214
	v_and_b32_e32 v227, 0xffff0000, v214
	v_lshlrev_b32_e32 v228, 16, v215
	v_and_b32_e32 v229, 0xffff0000, v215
	v_lshlrev_b32_e32 v230, 16, v216
	v_and_b32_e32 v231, 0xffff0000, v216
	v_lshlrev_b32_e32 v232, 16, v217
	v_and_b32_e32 v233, 0xffff0000, v217
	v_mul_f32_e32 v22, v22, v226
	v_mul_f32_e32 v23, v23, v227
	v_mul_f32_e32 v24, v24, v228
	v_mul_f32_e32 v25, v25, v229
	v_mul_f32_e32 v18, v18, v230
	v_mul_f32_e32 v19, v19, v231
	v_mul_f32_e32 v20, v20, v232
	v_mul_f32_e32 v21, v21, v233
	v_add_u32_e32 v235, 0x50000, v234
	v_cvt_pk_bf16_f32 v214, v22, v23
	v_cvt_pk_bf16_f32 v215, v24, v25
	v_cvt_pk_bf16_f32 v216, v18, v19
	v_cvt_pk_bf16_f32 v217, v20, v21
	global_store_dwordx4 v235, v[214:217], s[38:39] offset:256
	s_waitcnt vmcnt(15)
	v_lshlrev_b32_e32 v226, 16, v218
	v_and_b32_e32 v227, 0xffff0000, v218
	v_lshlrev_b32_e32 v228, 16, v219
	v_and_b32_e32 v229, 0xffff0000, v219
	v_lshlrev_b32_e32 v230, 16, v220
	v_and_b32_e32 v231, 0xffff0000, v220
	v_lshlrev_b32_e32 v232, 16, v221
	v_and_b32_e32 v233, 0xffff0000, v221
	v_mul_f32_e32 v14, v14, v226
	v_mul_f32_e32 v15, v15, v227
	v_mul_f32_e32 v16, v16, v228
	v_mul_f32_e32 v17, v17, v229
	v_mul_f32_e32 v10, v10, v230
	v_mul_f32_e32 v11, v11, v231
	v_mul_f32_e32 v12, v12, v232
	v_mul_f32_e32 v13, v13, v233
	v_add_u32_e32 v235, 0x58000, v234
	v_cvt_pk_bf16_f32 v218, v14, v15
	v_cvt_pk_bf16_f32 v219, v16, v17
	v_cvt_pk_bf16_f32 v220, v10, v11
	v_cvt_pk_bf16_f32 v221, v12, v13
	global_store_dwordx4 v235, v[218:221], s[38:39]
	s_waitcnt vmcnt(15)
	v_lshlrev_b32_e32 v226, 16, v222
	v_and_b32_e32 v227, 0xffff0000, v222
	v_lshlrev_b32_e32 v228, 16, v223
	v_and_b32_e32 v229, 0xffff0000, v223
	v_lshlrev_b32_e32 v230, 16, v224
	v_and_b32_e32 v231, 0xffff0000, v224
	v_lshlrev_b32_e32 v232, 16, v225
	v_and_b32_e32 v233, 0xffff0000, v225
	v_mul_f32_e32 v6, v6, v226
	v_mul_f32_e32 v7, v7, v227
	v_mul_f32_e32 v8, v8, v228
	v_mul_f32_e32 v9, v9, v229
	v_mul_f32_e32 v2, v2, v230
	v_mul_f32_e32 v3, v3, v231
	v_mul_f32_e32 v4, v4, v232
	v_mul_f32_e32 v5, v5, v233
	v_add_u32_e32 v235, 0x58000, v234
	v_cvt_pk_bf16_f32 v222, v6, v7
	v_cvt_pk_bf16_f32 v223, v8, v9
	v_cvt_pk_bf16_f32 v224, v2, v3
	v_cvt_pk_bf16_f32 v225, v4, v5
	global_store_dwordx4 v235, v[222:225], s[38:39] offset:256
	s_and_b64 vcc, exec, s[40:41]
	s_cbranch_vccnz .LBB0_612
; #define PG8_BAR __builtin_amdgcn_s_barrier()
;     __device__ __forceinline__ bool zero_after(const Unit& u) const { return (u.pm >> 6) == 3; }
; template <bool ALIGN_EPI, bool SP2, class Epi, class Sched>
; __device__ __forceinline__ void gemm_phase(LAS unsigned char* lds, const Gemm g, const Sched& S, const Epi& E) {
;     ...
;         if (!has_next) break;
;         if (E.zero_after(cur))
; #pragma unroll
;         for (int a = 0; a < 2; ++a)
; #pragma unroll
;             for (int b = 0; b < 2; ++b)
; #pragma unroll
;                 for (int m = 0; m < 4; ++m)
; #pragma unroll
;                     for (int n = 0; n < 2; ++n) acc[a][b][m][n] = (f32x4){0.f, 0.f, 0.f, 0.f};
;         cur = nxt; cA = nA; cB = nB; ++ui;
;         if constexpr (ALIGN_EPI) { if (wr == 1) PG8_BAR; }
	s_andn2_b64 vcc, exec, s[34:35]
	s_cbranch_vccnz .LBB0_611
	s_barrier
	s_branch .LBB0_611
